# phase 0 (weight prep): static s_setprio 1 for waves 4-7, reset before the phase barrier
# baseline (speedup 1.0000x reference)
; DI int otid() { int t = threadIdx.x; asm volatile("" : "+v"(t)); return t; }
; DI void narrow_item(const float* src, bf16_t* dst, int kt) {
;     const int tid = otid();
; #pragma unroll
;     for (int j = 0; j < 6; ++j) {
;         const int e = tid + 512 * j, kr = e / 48, cn = e % 48;
;         const int sc = cn < 32 ? 1024 + cn : 3104 + (cn - 32);
;         dst[(size_t)cn * 2048 + kt * 64 + kr] = f2bf(src[(size_t)(kt * 64 + kr) * INW + sc]);
;     }
; }
; DI void weight_prep_item(const P& q, int l, int it, unsigned char* sm) {
;     if (it < 96) adaln_item(q, l * 96 + it, sm);
;     else if (it < 96 + 896) { const int r = it - 96, kt = r / 28, nt = r % 28;
;         const int n0 = nt * 256, srcoff = n0 < 1024 ? 0 : (n0 < 3072 ? 32 : 48);
;         transpose_item(q.w_in + (size_t)l * DM * INW, INW, srcoff, (bf16_t*)(q.ws + WS_WINT) + (size_t)l * NP * DM, kt, nt, sm); }
;     else if (it < 96 + 896 + 256) { const int r = it - 96 - 896, kt = r / 8, nt = r % 8;
;         transpose_item(q.w_out + (size_t)l * DM * DM, DM, 0, (bf16_t*)(q.ws + WS_WOUTT) + (size_t)l * DM * DM, kt, nt, sm); }
;     else { const int kt = it - 96 - 896 - 256;
;         narrow_item(q.w_in + (size_t)l * DM * INW, (bf16_t*)(q.ws + WS_WNT) + (size_t)l * NNAR * DM, kt); }
; }
.LBB0_20:
	s_add_i32 s30, s30, s70
	s_cmpk_gt_i32 s30, 0x9ff
	s_cbranch_scc1 .LBB0_42
.LBB0_21:
	v_readfirstlane_b32 s98, v166
	s_nop 0
	s_lshr_b32 s98, s98, 6
	s_cmp_ge_u32 s98, 4
	s_cbranch_scc0 .Lp0_prio_done
	s_setprio 1
.Lp0_prio_done:
	s_mov_b64 s[24:25], 0
	s_add_u32 s24, s68, s24
	s_mov_b32 s6, 0
	s_addc_u32 s25, s69, s25
	s_add_i32 s62, s6, 0
	s_and_b32 s63, s30, 1
	s_ashr_i32 s64, s30, 1
	s_cmpk_gt_i32 s64, 0x5f
	s_mov_b64 s[26:27], -1
	s_cbranch_scc0 .LBB0_31
	s_cmpk_gt_u32 s64, 0x3df
	s_cbranch_scc0 .LBB0_28
	s_cmpk_gt_u32 s64, 0x4df
	s_cbranch_scc0 .LBB0_25
	v_mov_b32_e32 v1, v166
	s_mul_i32 s6, s63, 0x3860000
	v_mul_hi_i32 v0, v1, s31
	v_lshrrev_b32_e32 v2, 31, v0
	v_ashrrev_i32_e32 v0, 3, v0
	s_add_u32 s26, s12, s6
	v_add_u32_e32 v0, v0, v2
	s_addc_u32 s27, s13, 0
	s_mul_i32 s6, s63, 0x30000
	v_mul_lo_u32 v2, v0, 48
	s_add_u32 s28, s24, s6
	v_sub_u32_e32 v2, v1, v2
	s_addc_u32 s29, s25, 0
	s_lshl_b32 s6, s64, 6
	v_cmp_gt_i32_e32 vcc, 32, v2
	s_add_i32 s6, s6, 0xfffec800
	v_mov_b64_e32 v[4:5], s[26:27]
	v_cndmask_b32_e32 v3, v97, v167, vcc
	v_add_u32_e32 v76, v3, v2
	v_add_u32_e32 v3, s6, v0
	v_mad_i64_i32 v[6:7], s[26:27], v3, s36, v[4:5]
	v_add_u32_e32 v3, 0x200, v1
	v_mul_hi_i32 v8, v3, s31
	v_lshrrev_b32_e32 v9, 31, v8
	v_ashrrev_i32_e32 v8, 3, v8
	v_add_u32_e32 v8, v8, v9
	v_mul_lo_u32 v9, v8, 48
	v_sub_u32_e32 v10, v3, v9
	v_cmp_gt_i32_e32 vcc, 32, v10
	v_lshl_add_u64 v[6:7], v[76:77], 2, v[6:7]
	s_nop 0
	v_cndmask_b32_e32 v3, v97, v167, vcc
	v_add_u32_e32 v76, v3, v10
	v_add_u32_e32 v3, s6, v8
	v_mad_i64_i32 v[12:13], s[26:27], v3, s36, v[4:5]
	v_add_u32_e32 v3, 0x400, v1
	v_mul_hi_i32 v9, v3, s31
	v_lshrrev_b32_e32 v11, 31, v9
	v_ashrrev_i32_e32 v9, 3, v9
	v_add_u32_e32 v14, v9, v11
	v_mul_lo_u32 v9, v14, 48
	v_sub_u32_e32 v16, v3, v9
	v_cmp_gt_i32_e32 vcc, 32, v16
	v_lshl_add_u64 v[12:13], v[76:77], 2, v[12:13]
	v_add_u32_e32 v9, 0x600, v1
	v_cndmask_b32_e32 v3, v97, v167, vcc
	v_add_u32_e32 v76, v3, v16
	v_add_u32_e32 v3, s6, v14
	v_mad_i64_i32 v[18:19], s[26:27], v3, s36, v[4:5]
	v_lshl_add_u64 v[18:19], v[76:77], 2, v[18:19]
	global_load_dword v3, v[6:7], off
	s_nop 0
	global_load_dword v7, v[12:13], off
	s_nop 0
	global_load_dword v13, v[18:19], off
	v_mul_hi_i32 v6, v9, s31
	v_lshrrev_b32_e32 v11, 31, v6
	v_ashrrev_i32_e32 v6, 3, v6
	v_add_u32_e32 v6, v6, v11
	v_mul_lo_u32 v11, v6, 48
	v_sub_u32_e32 v12, v9, v11
	v_cmp_gt_i32_e32 vcc, 32, v12
	v_ashrrev_i32_e32 v17, 31, v16
	s_nop 0
	v_cndmask_b32_e32 v9, v97, v167, vcc
	v_add_u32_e32 v76, v9, v12
	v_add_u32_e32 v9, s6, v6
	v_mad_i64_i32 v[18:19], s[26:27], v9, s36, v[4:5]
	v_add_u32_e32 v9, 0x800, v1
	v_mul_hi_i32 v11, v9, s31
	v_lshrrev_b32_e32 v15, 31, v11
	v_ashrrev_i32_e32 v11, 3, v11
	v_add_u32_e32 v20, v11, v15
	v_mul_lo_u32 v11, v20, 48
	v_sub_u32_e32 v22, v9, v11
	v_cmp_gt_i32_e32 vcc, 32, v22
	v_lshl_add_u64 v[18:19], v[76:77], 2, v[18:19]
	v_add_u32_e32 v1, 0xa00, v1
	v_cndmask_b32_e32 v9, v97, v167, vcc
	v_add_u32_e32 v76, v9, v22
	v_add_u32_e32 v9, s6, v20
	v_mad_i64_i32 v[24:25], s[26:27], v9, s36, v[4:5]
	v_mul_hi_i32 v9, v1, s31
	v_lshrrev_b32_e32 v11, 31, v9
	v_ashrrev_i32_e32 v9, 3, v9
	v_lshl_add_u64 v[24:25], v[76:77], 2, v[24:25]
	global_load_dword v19, v[18:19], off
	s_nop 0
	global_load_dword v21, v[24:25], off
	v_add_u32_e32 v18, v9, v11
	v_mul_lo_u32 v9, v18, 48
	v_sub_u32_e32 v24, v1, v9
	v_cmp_gt_i32_e32 vcc, 32, v24
	v_ashrrev_i32_e32 v11, 31, v10
	v_ashrrev_i32_e32 v9, 31, v8
	v_cndmask_b32_e32 v1, v97, v167, vcc
	v_add_u32_e32 v76, v1, v24
	v_add_u32_e32 v1, s6, v18
	v_mad_i64_i32 v[4:5], s[26:27], v1, s36, v[4:5]
	v_lshl_add_u64 v[4:5], v[76:77], 2, v[4:5]
	global_load_dword v4, v[4:5], off
	s_lshl_b64 s[26:27], s[6:7], 1
	s_add_u32 s6, s28, s26
	s_addc_u32 s27, s29, s27
	s_add_u32 s26, s6, 0x17e4d200
	s_addc_u32 s27, s27, 0
	v_ashrrev_i32_e32 v1, 31, v0
	v_ashrrev_i32_e32 v15, 31, v14
	v_ashrrev_i32_e32 v23, 31, v22
	v_ashrrev_i32_e32 v25, 31, v24
	s_waitcnt vmcnt(5)
	v_cvt_pk_bf16_f32 v5, v3, s0
	v_ashrrev_i32_e32 v3, 31, v2
	v_lshlrev_b64 v[2:3], 12, v[2:3]
	v_lshl_add_u64 v[2:3], s[26:27], 0, v[2:3]
	v_lshl_add_u64 v[0:1], v[0:1], 1, v[2:3]
	global_store_short v[0:1], v5, off
	v_lshlrev_b64 v[0:1], 12, v[10:11]
	v_lshl_add_u64 v[0:1], s[26:27], 0, v[0:1]
	s_waitcnt vmcnt(5)
	v_cvt_pk_bf16_f32 v2, v7, s0
	v_lshl_add_u64 v[0:1], v[8:9], 1, v[0:1]
	global_store_short v[0:1], v2, off
	v_lshlrev_b64 v[0:1], 12, v[16:17]
	v_lshl_add_u64 v[0:1], s[26:27], 0, v[0:1]
	s_waitcnt vmcnt(5)
	v_cvt_pk_bf16_f32 v2, v13, s0
	v_lshl_add_u64 v[0:1], v[14:15], 1, v[0:1]
	v_ashrrev_i32_e32 v13, 31, v12
	global_store_short v[0:1], v2, off
	v_lshlrev_b64 v[0:1], 12, v[12:13]
	v_ashrrev_i32_e32 v7, 31, v6
	v_lshl_add_u64 v[0:1], s[26:27], 0, v[0:1]
	v_lshl_add_u64 v[0:1], v[6:7], 1, v[0:1]
	s_waitcnt vmcnt(5)
	v_cvt_pk_bf16_f32 v2, v19, s0
	global_store_short v[0:1], v2, off
	v_lshlrev_b64 v[0:1], 12, v[22:23]
	s_waitcnt vmcnt(5)
	v_cvt_pk_bf16_f32 v2, v21, s0
	v_ashrrev_i32_e32 v21, 31, v20
	v_lshl_add_u64 v[0:1], s[26:27], 0, v[0:1]
	v_lshl_add_u64 v[0:1], v[20:21], 1, v[0:1]
	global_store_short v[0:1], v2, off
	v_lshlrev_b64 v[0:1], 12, v[24:25]
	v_ashrrev_i32_e32 v19, 31, v18
	v_lshl_add_u64 v[0:1], s[26:27], 0, v[0:1]
	v_lshl_add_u64 v[0:1], v[18:19], 1, v[0:1]
	s_mov_b64 s[26:27], 0
	s_waitcnt vmcnt(5)
	v_cvt_pk_bf16_f32 v2, v4, s0
	global_store_short v[0:1], v2, off

; DI unsigned xb_ld(unsigned* p)              { return __hip_atomic_load(p, __ATOMIC_RELAXED, __HIP_MEMORY_SCOPE_AGENT); }
; DI void xcd_barrier_complete(unsigned* bar, unsigned x, unsigned& nloc, unsigned& nx) {
;     const unsigned G = gridDim.x * gridDim.y * gridDim.z;
;     unsigned sum, cnt, mine, sp = 0u;
;     for (;;) {
;         sum = 0u; cnt = 0u; mine = 0u;
; #pragma unroll
;         for (unsigned j = 0; j < 16; ++j) { const unsigned c = xb_ld(&bar[XB_XCNT(j)]); sum += c; cnt += (c > 0u) ? 1u : 0u; mine = (j == x) ? c : mine; }
;         if (sum == G) break;
;         __builtin_amdgcn_s_sleep(1);
;         if ((++sp & 255u) == 0u) { if (xb_ld(&bar[XB_TMO])) break; if (sp > XB_SPIN_CAP) { atomicAdd(&bar[XB_TMO], 1u); break; } }
;     }
;     nloc = mine > 0u ? mine : 1u; nx = cnt > 0u ? cnt : 1u;
; }
; DI void xcd_barrier(const XcdBarrier& b) {
;     asm volatile("s_waitcnt vmcnt(0)" ::: "memory");
;     __syncthreads();
;     if (threadIdx.x == 0) {
;         unsigned* bar = b.bar;
;         __builtin_amdgcn_s_waitcnt(0);
;         unsigned nloc = b.st[0], nx = b.st[1];
;         if (nloc == 0u) { xcd_barrier_complete(bar, b.x, nloc, nx); b.st[0] = nloc; b.st[1] = nx; }
.LBB0_42:
	s_setprio 0
	s_waitcnt vmcnt(0)
	s_barrier
	s_mov_b64 s[6:7], exec
	v_readlane_b32 s8, v253, 1
	v_readlane_b32 s9, v253, 2
	s_and_b64 s[8:9], s[6:7], s[8:9]
	s_mov_b64 exec, s[8:9]
	s_cbranch_execz .LBB0_94
	s_add_i32 s8, 0, 0x23ff0
	v_mov_b32_e32 v0, s8
	s_waitcnt vmcnt(0) expcnt(0) lgkmcnt(0)
	ds_read_b32 v2, v0
	s_add_i32 s8, 0, 0x23ff4
	v_mov_b32_e32 v0, s8
	ds_read_b32 v0, v0
	s_waitcnt lgkmcnt(1)
	v_cmp_ne_u32_e32 vcc, 0, v2
	s_cbranch_vccnz .LBB0_58
	s_add_u32 s8, s68, 0x1845d400
	s_addc_u32 s9, s69, 0
	s_add_u32 s10, s68, 0x1845d600
	s_addc_u32 s11, s69, 0
	s_add_u32 s12, s68, 0x1845d700
	s_addc_u32 s13, s69, 0
	s_add_u32 s14, s68, 0x1845d800
	s_addc_u32 s15, s69, 0
	s_add_u32 s16, s68, 0x1845d900
	s_addc_u32 s17, s69, 0
	s_add_u32 s18, s68, 0x1845da00
	s_addc_u32 s19, s69, 0
	s_add_u32 s20, s68, 0x1845db00
	s_addc_u32 s21, s69, 0
	s_add_u32 s22, s68, 0x1845dc00
	s_addc_u32 s23, s69, 0
	s_add_u32 s24, s68, 0x1845dd00
	s_addc_u32 s25, s69, 0
	s_add_u32 s26, s68, 0x1845de00
	s_addc_u32 s27, s69, 0
	s_add_u32 s28, s68, 0x1845df00
	s_addc_u32 s29, s69, 0
	s_add_u32 s30, s68, 0x1845e000
	s_addc_u32 s31, s69, 0
	s_add_u32 s34, s68, 0x1845e100
	s_addc_u32 s35, s69, 0
	s_add_u32 s36, s68, 0x1845e200
	s_addc_u32 s37, s69, 0
	s_add_u32 s38, s68, 0x1845e300
	s_addc_u32 s39, s69, 0
	s_add_u32 s40, s68, 0x1845e400
	s_addc_u32 s41, s69, 0
	s_mul_i32 s51, s71, s50
	s_add_u32 s42, s68, 0x1845e500
	s_mul_i32 s51, s51, s70
	s_addc_u32 s43, s69, 0
	s_mov_b32 s52, 1
	v_mov_b32_e32 v16, 0
	s_branch .LBB0_46
